# ph_mod: silu(c) table built from ten loads in flight per thread instead of ten serialized load-wait-silu-LDS round trips
# speedup vs baseline: 1.0095x; 1.0027x over previous
.LBB0_7:
.LBB0_8:
	v_readlane_b32 s8, v253, 0
	v_readlane_b32 s9, v253, 1
	s_mov_b64 s[16:17], s[8:9]
	s_load_dwordx4 s[4:7], s[16:17], 0x18
	s_load_dwordx2 s[10:11], s[16:17], 0x28
	s_load_dwordx2 s[0:1], s[16:17], 0x98
	v_mov_b32_e32 v2, v216
	s_load_dword s22, s[8:9], 0xb0
	s_add_u32 s8, s8, 0xb0
	s_movk_i32 s12, 0x1400
	v_readfirstlane_b32 s23, v2
	s_addc_u32 s9, s9, 0
	v_cmp_gt_i32_e32 vcc, s12, v2
	s_and_saveexec_b64 s[12:13], vcc
	s_cbranch_execz .LBB0_11
	s_load_dwordx2 s[18:19], s[16:17], 0x8
	v_lshlrev_b32_e32 v3, 2, v2
	v_lshl_add_u32 v1, v2, 2, 0
	v_add_u32_e32 v6, 0x1000, v3
	v_add_u32_e32 v7, 0x2000, v3
	v_add_u32_e32 v8, 0x3000, v3
	s_waitcnt lgkmcnt(0)
	global_load_dword v16, v3, s[18:19]
	global_load_dword v17, v3, s[18:19] offset:2048
	global_load_dword v18, v6, s[18:19]
	global_load_dword v19, v6, s[18:19] offset:2048
	global_load_dword v20, v7, s[18:19]
	global_load_dword v21, v7, s[18:19] offset:2048
	global_load_dword v22, v8, s[18:19]
	global_load_dword v23, v8, s[18:19] offset:2048
	global_load_dword v24, v3, s[4:5]
	global_load_dword v25, v3, s[4:5] offset:2048
	s_waitcnt vmcnt(9)
	v_mul_f32_e32 v9, 0xbfb8aa3b, v16
	v_exp_f32_e32 v9, v9
	s_nop 0
	v_add_f32_e32 v9, 1.0, v9
	v_rcp_f32_e32 v9, v9
	s_nop 0
	v_mul_f32_e32 v16, v16, v9
	ds_write_b32 v1, v16
	s_waitcnt vmcnt(8)
	v_mul_f32_e32 v9, 0xbfb8aa3b, v17
	v_exp_f32_e32 v9, v9
	s_nop 0
	v_add_f32_e32 v9, 1.0, v9
	v_rcp_f32_e32 v9, v9
	s_nop 0
	v_mul_f32_e32 v17, v17, v9
	ds_write_b32 v1, v17 offset:2048
	s_waitcnt vmcnt(7)
	v_mul_f32_e32 v9, 0xbfb8aa3b, v18
	v_exp_f32_e32 v9, v9
	s_nop 0
	v_add_f32_e32 v9, 1.0, v9
	v_rcp_f32_e32 v9, v9
	s_nop 0
	v_mul_f32_e32 v18, v18, v9
	ds_write_b32 v1, v18 offset:4096
	s_waitcnt vmcnt(6)
	v_mul_f32_e32 v9, 0xbfb8aa3b, v19
	v_exp_f32_e32 v9, v9
	s_nop 0
	v_add_f32_e32 v9, 1.0, v9
	v_rcp_f32_e32 v9, v9
	s_nop 0
	v_mul_f32_e32 v19, v19, v9
	ds_write_b32 v1, v19 offset:6144
	s_waitcnt vmcnt(5)
	v_mul_f32_e32 v9, 0xbfb8aa3b, v20
	v_exp_f32_e32 v9, v9
	s_nop 0
	v_add_f32_e32 v9, 1.0, v9
	v_rcp_f32_e32 v9, v9
	s_nop 0
	v_mul_f32_e32 v20, v20, v9
	ds_write_b32 v1, v20 offset:8192
	s_waitcnt vmcnt(4)
	v_mul_f32_e32 v9, 0xbfb8aa3b, v21
	v_exp_f32_e32 v9, v9
	s_nop 0
	v_add_f32_e32 v9, 1.0, v9
	v_rcp_f32_e32 v9, v9
	s_nop 0
	v_mul_f32_e32 v21, v21, v9
	ds_write_b32 v1, v21 offset:10240
	s_waitcnt vmcnt(3)
	v_mul_f32_e32 v9, 0xbfb8aa3b, v22
	v_exp_f32_e32 v9, v9
	s_nop 0
	v_add_f32_e32 v9, 1.0, v9
	v_rcp_f32_e32 v9, v9
	s_nop 0
	v_mul_f32_e32 v22, v22, v9
	ds_write_b32 v1, v22 offset:12288
	s_waitcnt vmcnt(2)
	v_mul_f32_e32 v9, 0xbfb8aa3b, v23
	v_exp_f32_e32 v9, v9
	s_nop 0
	v_add_f32_e32 v9, 1.0, v9
	v_rcp_f32_e32 v9, v9
	s_nop 0
	v_mul_f32_e32 v23, v23, v9
	ds_write_b32 v1, v23 offset:14336
	s_waitcnt vmcnt(1)
	v_mul_f32_e32 v9, 0xbfb8aa3b, v24
	v_exp_f32_e32 v9, v9
	s_nop 0
	v_add_f32_e32 v9, 1.0, v9
	v_rcp_f32_e32 v9, v9
	s_nop 0
	v_mul_f32_e32 v24, v24, v9
	ds_write_b32 v1, v24 offset:16384
	s_waitcnt vmcnt(0)
	v_mul_f32_e32 v9, 0xbfb8aa3b, v25
	v_exp_f32_e32 v9, v9
	s_nop 0
	v_add_f32_e32 v9, 1.0, v9
	v_rcp_f32_e32 v9, v9
	s_nop 0
	v_mul_f32_e32 v25, v25, v9
	ds_write_b32 v1, v25 offset:18432
